# E15: Fourier mixer mid rows (row S/2 reductions) moved from the 80 sample-DFT workgroups to the 176 prompt/gating workgroups; on N5 base
# baseline (speedup 1.0000x reference)
.LBB0_274:
	v_readlane_b32 s0, v252, 0
	v_readlane_b32 s1, v252, 1
	s_load_dwordx4 s[4:7], s[0:1], 0x70
	s_add_u32 s0, s90, 0x10000
	s_movk_i32 s82, 0xa0
	s_mov_b32 s62, -1
	s_mov_b32 s63, 0x20000
	s_waitcnt lgkmcnt(0)
	v_writelane_b32 v253, s4, 2
	v_mov_b32_e32 v147, 0
	v_mov_b32_e32 v209, 0x358637bd
	v_writelane_b32 v253, s5, 3
	v_writelane_b32 v253, s6, 4
	v_writelane_b32 v253, s7, 5
	v_writelane_b32 v253, s0, 10
	s_addc_u32 s0, s91, 0
	s_ashr_i32 s96, s3, 31
	s_ashr_i32 s83, s97, 31
	v_writelane_b32 v253, s0, 11
	s_add_u32 s0, s90, 0x4200
	s_addc_u32 s1, s91, 0
	s_add_u32 s52, s90, 0x4400
	s_addc_u32 s53, s91, 0
	s_add_u32 s68, s90, 0x4500
	v_writelane_b32 v252, s0, 28
	s_addc_u32 s69, s91, 0
	v_mov_b32_e32 v210, 0xbf1f24be
	v_writelane_b32 v252, s1, 29
	s_add_u32 s0, s90, 0x4600
	s_addc_u32 s1, s91, 0
	v_writelane_b32 v252, s0, 56
	v_mov_b32_e32 v211, 0x3e642e9d
	v_mov_b32_e32 v212, 8
	v_writelane_b32 v252, s1, 57
	s_add_u32 s0, s90, 0x4700
	s_addc_u32 s1, s91, 0
	v_writelane_b32 v252, s0, 62
	v_mov_b32_e32 v213, 3
	v_mov_b32_e32 v214, 0x204
	v_writelane_b32 v252, s1, 63
	s_add_u32 s0, s90, 0x4800
	s_addc_u32 s1, s91, 0
	v_writelane_b32 v253, s0, 0
	v_mov_b32_e32 v215, 0x3000
	v_mov_b32_e32 v216, 0x6000
	v_writelane_b32 v253, s1, 1
	s_add_u32 s0, s90, 0x4900
	s_addc_u32 s1, s91, 0
	v_writelane_b32 v252, s0, 52
	v_mov_b32_e32 v217, 0x9000
	v_mov_b32_e32 v218, 0xc000
	v_writelane_b32 v252, s1, 53
	s_add_u32 s0, s90, 0x4a00
	s_addc_u32 s1, s91, 0
	s_add_u32 s74, s90, 0x4b00
	v_writelane_b32 v253, s0, 6
	s_addc_u32 s75, s91, 0
	v_mov_b32_e32 v219, 0xf000
	v_writelane_b32 v253, s1, 7
	s_add_u32 s0, s90, 0x4c00
	s_addc_u32 s1, s91, 0
	s_add_u32 s4, s90, 0x4d00
	s_addc_u32 s5, s91, 0
	s_add_u32 s6, s90, 0x4e00
	s_addc_u32 s7, s91, 0
	s_add_u32 s54, s90, 0x4f00
	s_addc_u32 s55, s91, 0
	s_add_u32 s80, s90, 0x5000
	s_addc_u32 s81, s91, 0
	s_add_u32 s56, s90, 0x5100
	s_addc_u32 s57, s91, 0
	s_add_u32 s58, s90, 0x5200
	s_addc_u32 s59, s91, 0
	s_add_u32 s78, s90, 0x5300
	s_addc_u32 s79, s91, 0
	s_cmp_eq_u32 s13, 15
	s_cselect_b64 s[8:9], -1, 0
	v_writelane_b32 v253, s8, 12
	s_cmp_eq_u32 s13, 14
	v_mov_b32_e32 v220, 0x12000
	v_writelane_b32 v253, s9, 13
	s_cselect_b64 s[8:9], -1, 0
	v_writelane_b32 v253, s8, 14
	s_cmp_eq_u32 s13, 13
	v_mov_b32_e32 v221, 0x15000
	v_writelane_b32 v253, s9, 15
	s_cselect_b64 s[8:9], -1, 0
	v_writelane_b32 v253, s8, 16
	s_cmp_eq_u32 s13, 12
	v_mbcnt_hi_u32_b32 v222, -1, v63
	v_writelane_b32 v253, s9, 17
	s_cselect_b64 s[8:9], -1, 0
	v_writelane_b32 v253, s8, 18
	s_cmp_eq_u32 s13, 11
	v_mov_b32_e32 v223, 0x7fc00000
	v_writelane_b32 v253, s9, 19
	s_cselect_b64 s[8:9], -1, 0
	v_writelane_b32 v253, s8, 20
	s_cmp_eq_u32 s13, 10
	v_mov_b64_e32 v[150:151], 0x500
	v_writelane_b32 v253, s9, 21
	s_cselect_b64 s[8:9], -1, 0
	v_writelane_b32 v253, s8, 22
	s_cmp_eq_u32 s13, 9
	v_mov_b64_e32 v[152:153], 0x4ff
	v_writelane_b32 v253, s9, 23
	s_cselect_b64 s[8:9], -1, 0
	v_writelane_b32 v253, s8, 24
	s_cmp_eq_u32 s13, 8
	v_mov_b64_e32 v[226:227], 0xf00
	v_writelane_b32 v253, s9, 25
	s_cselect_b64 s[8:9], -1, 0
	v_writelane_b32 v253, s8, 26
	s_cmp_eq_u32 s13, 7
	v_mov_b64_e32 v[148:149], 0xeff
	v_writelane_b32 v253, s9, 27
	s_cselect_b64 s[8:9], -1, 0
	v_writelane_b32 v253, s8, 28
	s_cmp_eq_u32 s13, 6
	v_mov_b64_e32 v[158:159], 0x280
	v_writelane_b32 v253, s9, 29
	s_cselect_b64 s[8:9], -1, 0
	v_writelane_b32 v253, s8, 30
	s_cmp_eq_u32 s13, 5
	v_mov_b64_e32 v[160:161], 0x27f
	v_writelane_b32 v253, s9, 31
	s_cselect_b64 s[8:9], -1, 0
	v_writelane_b32 v253, s8, 32
	s_cmp_eq_u32 s13, 4
	v_mov_b32_e32 v224, 0x2000
	v_writelane_b32 v253, s9, 33
	s_cselect_b64 s[8:9], -1, 0
	v_writelane_b32 v253, s8, 34
	s_cmp_eq_u32 s13, 3
	v_mov_b32_e32 v225, 0x800
	v_writelane_b32 v253, s9, 35
	s_cselect_b64 s[8:9], -1, 0
	v_writelane_b32 v253, s8, 36
	s_cmp_eq_u32 s13, 2
	v_mov_b64_e32 v[162:163], 0xc0
	v_writelane_b32 v253, s9, 37
	s_cselect_b64 s[8:9], -1, 0
	v_writelane_b32 v253, s8, 38
	s_cmp_eq_u32 s13, 1
	v_mov_b64_e32 v[164:165], 0xbf
	v_writelane_b32 v253, s9, 39
	s_cselect_b64 s[8:9], -1, 0
	v_writelane_b32 v253, s8, 40
	s_cmp_eq_u32 s13, 0
	v_mov_b64_e32 v[166:167], 0x80
	v_writelane_b32 v253, s9, 41
	s_cselect_b64 s[8:9], -1, 0
	v_writelane_b32 v253, s8, 42
	v_mov_b64_e32 v[168:169], 0x7f
	s_mov_b32 s51, 0x33300000
	v_writelane_b32 v253, s9, 43
	s_lshl_b64 s[8:9], s[16:17], 2
	s_add_u32 s2, s48, s8
	s_addc_u32 s8, s49, s9
	s_add_u32 s10, s2, 0x1400
	s_addc_u32 s11, s8, 0
	v_writelane_b32 v253, s10, 44
	s_movk_i32 s76, 0x7fff
	s_mov_b32 s77, 0xffff0000
	v_writelane_b32 v253, s11, 45
	s_add_u32 s10, s90, 0x7400
	s_addc_u32 s11, s91, 0
	v_writelane_b32 v253, s10, 46
	s_mov_b32 s50, 0x3b3504f3
	s_nop 0
	v_writelane_b32 v253, s11, 47
	s_add_u32 s10, s90, 0x7500
	s_addc_u32 s11, s91, 0
	v_writelane_b32 v252, s10, 32
	s_nop 1
	v_writelane_b32 v252, s11, 33
	s_add_u32 s10, s2, 0x2400
	s_addc_u32 s11, s8, 0
	s_cmpk_lt_i32 s97, 0x500
	s_cselect_b64 s[8:9], -1, 0
	s_lshr_b32 s2, s83, 29
	v_writelane_b32 v253, s8, 48
	s_add_i32 s2, s97, s2
	s_ashr_i32 s21, s2, 3
	v_writelane_b32 v253, s9, 49
	s_and_b32 s8, s2, -8
	s_sub_i32 s20, s97, s8
	s_cmp_gt_i32 s20, -1
	v_writelane_b32 v252, s10, 34
	s_cselect_b64 s[8:9], -1, 0
	s_nop 0
	v_writelane_b32 v252, s11, 35
	s_and_b64 s[10:11], s[8:9], exec
	s_cselect_b32 s2, s82, 0xa1
	s_cmp_lg_u64 s[8:9], 0
	s_mul_i32 s2, s20, s2
	s_subb_u32 s8, 0, s21
	s_add_i32 s11, s8, s2
	s_cmpk_lt_i32 s97, 0xf00
	s_cselect_b64 s[8:9], -1, 0
	s_lshr_b32 s2, s3, 31
	v_writelane_b32 v253, s8, 50
	s_add_i32 s2, s3, s2
	s_ashr_i32 s10, s2, 1
	v_writelane_b32 v253, s9, 51
	s_ashr_i32 s2, s12, 5
	v_writelane_b32 v253, s2, 52
	s_mulk_i32 s2, 0x280
	s_addk_i32 s2, 0x27f
	v_writelane_b32 v253, s2, 53
	s_lshl_b32 s2, s12, 1
	v_writelane_b32 v253, s2, 54
	s_and_b32 s2, s2, 62
	s_add_i32 s10, s10, s97
	v_writelane_b32 v253, s2, 55
	s_lshl_b32 s2, s3, 1
	s_cmp_gt_i32 s97, -1
	s_cselect_b64 s[12:13], -1, 0
	s_cmpk_eq_i32 s3, 0x100
	s_cselect_b64 s[30:31], -1, 0
	s_and_b64 s[8:9], s[30:31], exec
	s_cselect_b32 s25, 48, s3
	v_writelane_b32 v253, s2, 56
	s_cselect_b32 s2, 0xffffffd0, 0
	s_cselect_b32 s14, 48, 0
	s_cselect_b32 s26, 32, s3
	s_cselect_b32 s22, 0xffffffb0, 0
	s_cselect_b32 s23, 0x50, 0
	s_cselect_b32 s27, 0xb0, s3
	s_cselect_b32 s24, 0x50, s3
	s_cmp_lt_i32 s97, s25
	s_cselect_b64 s[8:9], -1, 0
	s_and_b64 s[8:9], s[12:13], s[8:9]
	v_writelane_b32 v253, s8, 57
	s_nop 1
	v_writelane_b32 v253, s9, 58
	s_ashr_i32 s8, s25, 31
	s_cmp_ge_i32 s97, s14
	v_writelane_b32 v253, s8, 59
	s_cselect_b64 s[8:9], -1, 0
	s_cmp_lt_i32 s97, s24
	s_cselect_b64 s[14:15], -1, 0
	s_and_b64 s[8:9], s[8:9], s[14:15]
	v_writelane_b32 v253, s8, 60
	s_nop 1
	v_writelane_b32 v253, s9, 61
	s_add_i32 s9, s2, s97
	s_ashr_i32 s2, s26, 31
	s_cmp_ge_i32 s97, s23
	s_cselect_b64 s[16:17], -1, 0
	s_cmp_lt_i32 s97, s3
	s_cselect_b64 s[18:19], -1, 0
	v_writelane_b32 v253, s2, 62
	s_and_b64 s[16:17], s[18:19], s[16:17]
	v_writelane_b32 v253, s16, 63
	s_mov_b64 s[12:13], s[16:17]
	s_lshl_b32 s2, s27, 3
	v_writelane_b32 v254, s17, 0
	v_writelane_b32 v254, s12, 1
	s_add_i32 s8, s22, s97
	s_and_b32 s18, s97, 15
	v_writelane_b32 v254, s13, 2
	s_sub_i32 s12, s97, s23
	s_ashr_i32 s13, s27, 31
	v_writelane_b32 v254, s2, 3
	s_add_i32 s2, s23, s97
	v_writelane_b32 v252, s13, 50
	s_lshl_b32 s13, s12, 3
	s_ashr_i32 s22, s12, 4
	s_ashr_i32 s24, s27, 4
	s_cmp_gt_i32 s12, -1
	v_writelane_b32 v254, s13, 4
	s_cselect_b64 s[14:15], -1, 0
	s_and_b32 s13, s27, -16
	s_cmp_lt_i32 s12, s13
	s_cselect_b64 s[12:13], -1, 0
	s_cmp_gt_u32 s27, 15
	s_cselect_b64 s[16:17], -1, 0
	s_and_b64 s[16:17], s[16:17], s[12:13]
	s_lshl_b32 s12, s18, 7
	s_cmpk_lt_i32 s22, 0x140
	v_writelane_b32 v254, s12, 5
	s_cselect_b64 s[12:13], -1, 0
	v_writelane_b32 v254, s12, 6
	s_addk_i32 s11, 0xa0
	s_nop 0
	v_writelane_b32 v254, s13, 7
	s_ashr_i32 s12, s11, 31
	s_lshr_b32 s12, s12, 27
	s_add_i32 s12, s11, s12
	s_and_b32 s13, s12, 0xffffffe0
	s_ashr_i32 s12, s12, 5
	s_sub_i32 s11, s11, s13
	s_lshl_b32 s13, s18, 6
	s_lshl_b32 s12, s12, 2
	v_writelane_b32 v254, s13, 8
	s_sub_i32 s13, 0xa0, s12
	s_min_i32 s13, s13, 4
	s_cmp_lt_i32 s20, 0
	s_movk_i32 s18, 0x1e1
	s_cselect_b32 s18, s18, 0x1e0
	s_cselect_b32 s19, 0xa1, s82
	s_and_b64 s[14:15], s[14:15], s[16:17]
	v_writelane_b32 v254, s14, 9
	s_nop 1
	v_writelane_b32 v254, s15, 10
	s_mul_i32 s14, s20, s18
	s_add_i32 s14, s14, s21
	s_mul_hi_i32 s15, s14, 0x2aaaaaab
	s_lshr_b32 s16, s15, 31
	s_ashr_i32 s15, s15, 4
	s_add_i32 s15, s15, s16
	s_mul_i32 s16, s15, 0x60
	s_sub_i32 s14, s14, s16
	s_bfe_i32 s16, s14, 0x80000
	s_bfe_u32 s16, s16, 0x2000d
	s_add_i32 s16, s14, s16
	s_and_b32 s17, s16, 0xfc
	s_sub_i32 s14, s14, s17
	s_lshl_b32 s15, s15, 2
	s_sext_i32_i8 s14, s14
	s_add_i32 s23, s15, s14
	s_mul_i32 s14, s20, s19
	s_add_i32 s14, s14, s21
	s_mul_hi_i32 s15, s14, 0x66666667
	s_lshr_b32 s17, s15, 31
	s_ashr_i32 s15, s15, 8
	s_add_i32 s15, s15, s17
	s_mul_i32 s17, s15, 0x280
	s_sub_i32 s17, s14, s17
	s_bfe_u32 s18, s17, 0x2001d
	s_add_i32 s18, s17, s18
	s_and_b32 s19, s18, 0xfffc
	s_sub_i32 s17, s17, s19
	s_lshl_b32 s15, s15, 2
	s_sext_i32_i16 s17, s17
	s_add_i32 s20, s15, s17
	s_ashr_i32 s15, s14, 31
	s_lshr_b32 s15, s15, 27
	s_add_i32 s15, s14, s15
	s_and_b32 s17, s15, 0xffe0
	s_sub_i32 s14, s14, s17
	s_bfe_i32 s17, s14, 0x80000
	s_bfe_u32 s17, s17, 0x2000d
	s_add_i32 s17, s14, s17
	s_and_b32 s19, s17, 0xfc
	s_sub_i32 s14, s14, s19
	s_ashr_i32 s15, s15, 5
	s_lshl_b32 s15, s15, 2
	s_sext_i32_i8 s14, s14
	s_add_i32 s21, s15, s14
	s_abs_i32 s14, s3
	v_cvt_f32_u32_e32 v1, s14
	s_sub_i32 s15, 0, s14
	s_bfe_i32 s16, s16, 0x80000
	s_sext_i32_i16 s16, s16
	v_rcp_iflag_f32_e32 v1, v1
	s_nop 0
	v_mul_f32_e32 v1, 0x4f7ffffe, v1
	v_cvt_u32_f32_e32 v1, v1
	s_nop 0
	v_readfirstlane_b32 s19, v1
	s_mul_i32 s15, s15, s19
	s_mul_hi_u32 s15, s19, s15
	s_add_i32 s15, s19, s15
	s_ashr_i32 s19, s16, 2
	v_writelane_b32 v254, s19, 11
	s_lshl_b32 s19, s19, 20
	s_or_b32 s29, s19, 0x80000
	v_writelane_b32 v254, s29, 12
	v_writelane_b32 v254, s23, 13
	s_lshl_b32 s23, s23, 20
	s_or_b32 s29, s23, 0x80000
	v_writelane_b32 v254, s29, 14
	s_or_b32 s29, s19, 0x80
	v_writelane_b32 v254, s29, 15
	v_writelane_b32 v254, s23, 16
	s_bitset1_b32 s23, 7
	v_writelane_b32 v254, s23, 17
	s_sext_i32_i16 s16, s18
	v_writelane_b32 v254, s19, 18
	s_or_b32 s19, s19, 0x80080
	s_ashr_i32 s18, s16, 2
	v_writelane_b32 v254, s19, 19
	v_writelane_b32 v254, s18, 20
	s_lshl_b32 s18, s18, 20
	s_or_b32 s19, s18, 0x80000
	v_writelane_b32 v254, s19, 21
	s_lshl_b32 s19, s20, 20
	v_writelane_b32 v254, s20, 22
	s_or_b32 s20, s19, 0x80000
	v_writelane_b32 v254, s20, 23
	s_or_b32 s20, s18, 0x80
	v_writelane_b32 v254, s20, 24
	s_bfe_i32 s16, s17, 0x80000
	v_writelane_b32 v254, s19, 25
	s_bitset1_b32 s19, 7
	s_sext_i32_i16 s16, s16
	v_writelane_b32 v254, s19, 26
	s_ashr_i32 s28, s16, 2
	v_writelane_b32 v254, s18, 27
	s_or_b32 s18, s18, 0x80080
	v_writelane_b32 v254, s18, 28
	s_lshl_b32 s18, s28, 20
	s_or_b32 s19, s18, 0x80000
	v_writelane_b32 v254, s19, 29
	s_lshl_b32 s19, s21, 20
	s_or_b32 s20, s19, 0x80000
	v_writelane_b32 v254, s20, 30
	s_or_b32 s20, s18, 0x80
	v_writelane_b32 v254, s20, 31
	v_writelane_b32 v254, s19, 32
	s_bitset1_b32 s19, 7
	v_writelane_b32 v254, s19, 33
	v_writelane_b32 v254, s18, 34
	s_or_b32 s18, s18, 0x80080
	v_writelane_b32 v254, s18, 35
	s_mul_i32 s18, s28, 0x2c0000
	v_writelane_b32 v254, s28, 36
	s_add_i32 s19, s18, 0x160000
	v_writelane_b32 v254, s19, 37
	s_mul_i32 s19, s21, 0x2c0000
	v_writelane_b32 v254, s21, 38
	s_or_b32 s20, s19, 0x4000
	v_writelane_b32 v254, s20, 39
	s_or_b32 s20, s18, 0x80
	v_writelane_b32 v254, s20, 40
	s_mul_hi_u32 s16, s15, 0x1b80
	v_writelane_b32 v254, s19, 41
	s_bitset1_b32 s19, 15
	s_mul_i32 s17, s16, s14
	v_writelane_b32 v254, s19, 42
	s_sub_i32 s17, 0x1b80, s17
	v_writelane_b32 v254, s18, 43
	s_add_i32 s18, s18, 0x160080
	v_writelane_b32 v254, s18, 44
	s_add_i32 s18, s16, 1
	s_sub_i32 s19, s17, s14
	s_cmp_ge_u32 s17, s14
	s_cselect_b32 s16, s18, s16
	s_cselect_b32 s17, s19, s17
	s_add_i32 s18, s16, 1
	s_cmp_ge_u32 s17, s14
	s_cselect_b32 s16, s18, s16
	s_xor_b32 s16, s16, s96
	s_sub_i32 s28, s16, s96
	s_cmp_eq_u32 s28, 1
	v_readlane_b32 s18, v252, 10
	s_cselect_b64 s[16:17], -1, 0
	v_readlane_b32 s19, v252, 11
	s_and_b64 s[16:17], s[18:19], s[16:17]
	v_writelane_b32 v254, s16, 45
	s_cmp_lt_i32 s28, 1
	s_nop 0
	v_writelane_b32 v254, s17, 46
	s_cselect_b64 s[16:17], -1, 0
	v_writelane_b32 v254, s16, 47
	s_cmp_gt_i32 s28, -1
	s_nop 0
	v_writelane_b32 v254, s17, 48
	s_cselect_b64 s[16:17], -1, 0
	v_writelane_b32 v254, s16, 49
	s_add_i32 s20, s28, -2
	v_writelane_b32 v252, s20, 60
	v_writelane_b32 v254, s17, 50
	s_abs_i32 s16, s13
	v_cvt_f32_u32_e32 v1, s16
	s_sub_i32 s17, 0, s16
	v_writelane_b32 v252, s27, 48
	v_writelane_b32 v252, s28, 20
	v_rcp_iflag_f32_e32 v1, v1
	s_nop 0
	v_mul_f32_e32 v1, 0x4f7ffffe, v1
	v_cvt_u32_f32_e32 v1, v1
	s_nop 0
	v_readfirstlane_b32 s18, v1
	s_mul_i32 s17, s17, s18
	s_mul_hi_u32 s17, s18, s17
	s_add_i32 s18, s18, s17
	s_abs_i32 s17, s11
	s_mul_hi_u32 s18, s17, s18
	s_mul_i32 s19, s18, s16
	s_sub_i32 s17, s17, s19
	s_xor_b32 s19, s11, s13
	s_ashr_i32 s19, s19, 31
	s_add_i32 s20, s18, 1
	s_sub_i32 s21, s17, s16
	s_cmp_ge_u32 s17, s16
	s_cselect_b32 s18, s20, s18
	s_cselect_b32 s17, s21, s17
	s_add_i32 s20, s18, 1
	s_cmp_ge_u32 s17, s16
	s_cselect_b32 s16, s20, s18
	s_xor_b32 s16, s16, s19
	s_sub_i32 s16, s16, s19
	s_mul_i32 s13, s16, s13
	s_sub_i32 s11, s11, s13
	s_add_i32 s17, s12, s11
	s_abs_i32 s11, s10
	s_mul_hi_u32 s12, s11, s15
	s_mul_i32 s12, s12, s14
	s_sub_i32 s11, s11, s12
	s_mul_i32 s12, s16, 0x2c0000
	s_add_i32 s13, s12, 0x160000
	v_writelane_b32 v254, s13, 51
	s_mul_i32 s13, s17, 0x2c0000
	s_or_b32 s15, s13, 0x4000
	v_writelane_b32 v254, s15, 52
	s_or_b32 s15, s12, 0x80
	v_writelane_b32 v254, s15, 53
	v_writelane_b32 v254, s13, 54
	s_bitset1_b32 s13, 15
	v_writelane_b32 v254, s13, 55
	v_writelane_b32 v254, s12, 56
	s_add_i32 s12, s12, 0x160080
	s_ashr_i32 s10, s10, 31
	v_writelane_b32 v254, s12, 57
	s_sub_i32 s12, s11, s14
	s_cmp_ge_u32 s11, s14
	s_cselect_b32 s11, s12, s11
	s_sub_i32 s12, s11, s14
	s_cmp_ge_u32 s11, s14
	s_cselect_b32 s11, s12, s11
	s_xor_b32 s11, s11, s10
	s_sub_i32 s12, s11, s10
	s_cmpk_lt_i32 s12, 0x280
	s_cselect_b64 s[10:11], -1, 0
	v_writelane_b32 v254, s10, 58
	s_mov_b32 s20, 0x3ab504f3
	s_nop 0
	v_writelane_b32 v254, s11, 59
	s_ashr_i32 s10, s12, 31
	v_writelane_b32 v254, s10, 60
	s_lshr_b32 s10, s10, 29
	s_add_i32 s10, s12, s10
	s_ashr_i32 s11, s10, 3
	s_and_b32 s10, s10, -8
	s_sub_i32 s10, s12, s10
	v_writelane_b32 v254, s12, 61
	s_cmp_lt_i32 s10, 0
	s_movk_i32 s12, 0x51
	s_cselect_b32 s12, s12, 0x50
	s_mul_i32 s10, s10, s12
	s_add_i32 s10, s10, s11
	s_ashr_i32 s11, s10, 31
	s_lshr_b32 s11, s11, 28
	s_add_i32 s11, s10, s11
	s_and_b32 s12, s11, 0xfff0
	s_sub_i32 s10, s10, s12
	s_bfe_i32 s12, s10, 0x80000
	s_bfe_u32 s12, s12, 0x2000d
	s_add_i32 s12, s10, s12
	s_and_b32 s13, s12, 0xfc
	s_sub_i32 s10, s10, s13
	s_ashr_i32 s11, s11, 4
	s_lshl_b32 s11, s11, 2
	s_sext_i32_i8 s10, s10
	s_add_i32 s14, s11, s10
	s_abs_i32 s10, s25
	v_cvt_f32_u32_e32 v1, s10
	s_sub_i32 s11, 0, s10
	s_bfe_i32 s12, s12, 0x80000
	s_sext_i32_i16 s12, s12
	v_rcp_iflag_f32_e32 v1, v1
	v_writelane_b32 v254, s25, 62
	s_ashr_i32 s12, s12, 2
	v_writelane_b32 v254, s12, 63
	v_mul_f32_e32 v1, 0x4f7ffffe, v1
	v_cvt_u32_f32_e32 v1, v1
	s_lshl_b32 s12, s12, 20
	v_readfirstlane_b32 s13, v1
	s_mul_i32 s11, s11, s13
	s_mul_hi_u32 s11, s13, s11
	s_add_i32 s13, s13, s11
	s_abs_i32 s11, s97
	s_mul_hi_u32 s13, s11, s13
	s_mul_i32 s13, s13, s10
	s_sub_i32 s11, s11, s13
	s_or_b32 s13, s12, 0x80000
	v_writelane_b32 v255, s13, 0
	s_lshl_b32 s13, s14, 20
	v_writelane_b32 v255, s14, 1
	s_or_b32 s14, s13, 0x80000
	v_writelane_b32 v255, s14, 2
	s_or_b32 s14, s12, 0x80
	v_writelane_b32 v255, s14, 3
	v_writelane_b32 v255, s13, 4
	s_bitset1_b32 s13, 7
	v_writelane_b32 v255, s13, 5
	v_writelane_b32 v255, s12, 6
	s_or_b32 s12, s12, 0x80080
	v_writelane_b32 v255, s12, 7
	s_sub_i32 s12, s11, s10
	s_cmp_ge_u32 s11, s10
	s_cselect_b32 s11, s12, s11
	s_sub_i32 s12, s11, s10
	s_cmp_ge_u32 s11, s10
	s_cselect_b32 s10, s12, s11
	s_abs_i32 s11, s26
	v_cvt_f32_u32_e32 v1, s11
	s_sub_i32 s12, 0, s11
	s_xor_b32 s10, s10, s83
	v_writelane_b32 v255, s26, 8
	v_rcp_iflag_f32_e32 v1, v1
	s_sub_i32 s10, s10, s83
	v_writelane_b32 v255, s10, 9
	v_mul_f32_e32 v1, 0x4f7ffffe, v1
	v_cvt_u32_f32_e32 v1, v1
	s_nop 0
	v_readfirstlane_b32 s13, v1
	s_mul_i32 s12, s12, s13
	s_mul_hi_u32 s12, s13, s12
	s_add_i32 s13, s13, s12
	s_abs_i32 s12, s9
	s_mul_hi_u32 s13, s12, s13
	s_mul_i32 s13, s13, s11
	s_sub_i32 s12, s12, s13
	s_ashr_i32 s9, s9, 31
	s_sub_i32 s10, s12, s11
	s_cmp_ge_u32 s12, s11
	s_cselect_b32 s10, s10, s12
	s_sub_i32 s12, s10, s11
	s_cmp_ge_u32 s10, s11
	s_cselect_b32 s10, s12, s10
	s_xor_b32 s10, s10, s9
	s_sub_i32 s9, s10, s9
	v_writelane_b32 v255, s9, 10
	s_abs_i32 s9, s27
	v_cvt_f32_u32_e32 v1, s9
	s_sub_i32 s10, 0, s9
	v_rcp_iflag_f32_e32 v1, v1
	s_nop 0
	v_mul_f32_e32 v1, 0x4f7ffffe, v1
	v_cvt_u32_f32_e32 v1, v1
	s_nop 0
	v_readfirstlane_b32 s11, v1
	s_mul_i32 s10, s10, s11
	s_mul_hi_u32 s10, s11, s10
	s_add_i32 s11, s11, s10
	s_abs_i32 s10, s8
	s_mul_hi_u32 s12, s10, s11
	s_mul_i32 s12, s12, s9
	s_sub_i32 s10, s10, s12
	s_ashr_i32 s8, s8, 31
	s_sub_i32 s12, s10, s9
	s_cmp_ge_u32 s10, s9
	s_cselect_b32 s10, s12, s10
	s_sub_i32 s12, s10, s9
	s_cmp_ge_u32 s10, s9
	s_cselect_b32 s10, s12, s10
	s_xor_b32 s10, s10, s8
	s_sub_i32 s8, s10, s8
	v_writelane_b32 v255, s8, 11
	s_abs_i32 s8, s2
	s_mul_hi_u32 s10, s8, s11
	s_mul_i32 s10, s10, s9
	s_sub_i32 s8, s8, s10
	s_ashr_i32 s2, s2, 31
	s_sub_i32 s10, s8, s9
	s_cmp_ge_u32 s8, s9
	s_cselect_b32 s8, s10, s8
	s_sub_i32 s10, s8, s9
	s_cmp_ge_u32 s8, s9
	s_cselect_b32 s8, s10, s8
	s_xor_b32 s8, s8, s2
	s_sub_i32 s2, s8, s2
	v_writelane_b32 v255, s2, 12
	s_mul_hi_i32 s2, s28, s3
	v_writelane_b32 v255, s2, 13
	s_mul_i32 s2, s28, s3
	v_writelane_b32 v255, s2, 14
	s_lshl_b32 s2, s16, 20
	v_writelane_b32 v255, s16, 15
	s_or_b32 s8, s2, 0x80000
	v_writelane_b32 v255, s8, 16
	s_lshl_b32 s8, s17, 20
	v_writelane_b32 v255, s17, 17
	s_or_b32 s9, s8, 0x80000
	v_writelane_b32 v255, s9, 18
	s_or_b32 s9, s2, 0x80
	v_writelane_b32 v255, s9, 19
	v_writelane_b32 v255, s8, 20
	s_bitset1_b32 s8, 7
	v_writelane_b32 v255, s8, 21
	s_ashr_i32 s23, s22, 31
	v_writelane_b32 v255, s2, 22
	s_or_b32 s2, s2, 0x80080
	v_writelane_b32 v255, s2, 23
	s_lshl_b64 s[12:13], s[22:23], 19
	s_ashr_i32 s25, s24, 31
	v_writelane_b32 v255, s12, 24
	s_add_i32 s2, 0, 0x20060
	v_writelane_b32 v253, s2, 8
	v_writelane_b32 v255, s13, 25
	s_lshl_b64 s[12:13], s[24:25], 19
	v_writelane_b32 v255, s12, 26
	s_add_i32 s2, 0, 0x20048
	v_writelane_b32 v252, s2, 26
	v_writelane_b32 v255, s13, 27
	s_lshl_b64 s[12:13], s[22:23], 18
	v_writelane_b32 v255, s12, 28
	s_add_i32 s2, 0, 0x20044
	v_writelane_b32 v252, s2, 22
	v_writelane_b32 v255, s13, 29
	s_lshl_b64 s[12:13], s[24:25], 18
	s_add_i32 s2, 0, 0x20040
	v_writelane_b32 v255, s12, 30
	v_writelane_b32 v252, s2, 24
	s_add_i32 s2, 0, 0x20020
	v_writelane_b32 v255, s13, 31
	s_lshl_b64 s[12:13], s[22:23], 7
	v_writelane_b32 v252, s2, 40
	s_add_i32 s2, 0, 0x20024
	v_writelane_b32 v255, s12, 32
	v_writelane_b32 v252, s2, 42
	s_mov_b32 s2, s22
	v_writelane_b32 v255, s13, 33
	v_writelane_b32 v255, s2, 34
	s_lshl_b64 s[12:13], s[22:23], 8
	v_writelane_b32 v252, s96, 46
	v_writelane_b32 v255, s3, 35
	v_writelane_b32 v255, s12, 36
	v_writelane_b32 v252, s83, 30
	v_writelane_b32 v252, s52, 36
	v_writelane_b32 v255, s13, 37
	s_lshl_b64 s[12:13], s[24:25], 8
	v_writelane_b32 v255, s12, 38
	v_writelane_b32 v252, s53, 37
	v_writelane_b32 v252, s68, 38
	v_writelane_b32 v255, s13, 39
	v_writelane_b32 v255, s30, 40
	v_mov_b32_e32 v1, 1
	s_movk_i32 s10, 0x1000
	v_writelane_b32 v255, s31, 41
	v_writelane_b32 v255, s24, 42
	s_mov_b32 s11, 0x49800000
	s_mov_b32 s8, 0
	s_mov_b32 s17, 0
	s_mov_b64 s[28:29], 0x1000
	v_writelane_b32 v252, s69, 39
	v_writelane_b32 v255, s25, 43
	s_branch .LBB0_279
